# cmp phase selection loop: the four Q fragment loads of a head issued together with counted waits instead of three serialised load/wait round trips
# baseline (speedup 1.0000x reference)
; __device__ __forceinline__ int crow(int r, int hi) { return (r & 3) + 8 * (r >> 2) + 4 * hi; }
; __device__ __forceinline__ void cmp_phase(LAS unsigned char* lds, const bf16_t* __restrict__ P, const bf16_t* __restrict__ Kc, const bf16_t* __restrict__ Vc,
;                                           bf16_t* __restrict__ ocmp, unsigned long long* __restrict__ mask, int G, const int wave0) {
;     ...
;                 for (int hh = 0; hh < 4; ++hh) {
;                     const int head = 4 * g + hh;
;                     bf16x8 qf[4];
; #pragma unroll
;                     for (int ds = 0; ds < 4; ++ds) qf[ds] = *(const bf16x8*)(P + row * NPJ + C_NQ + head * 64 + 16 * ds + 8 * hi);
;                     CMP_QK(c)
;                     const float m_h = mi[(hh * 32 + r32) * 2], i_h = mi[(hh * 32 + r32) * 2 + 1];
;                     if (16 * (64 * c + 63) + 31 > tw0) {
; #pragma unroll
;                         for (int r = 0; r < 16; ++r) {
;                             const int nc = 64 * c + crow(r, hi);
;                             p0[r] = (16 * nc + 31 <= tq) ? p0[r] : -INFINITY; p1[r] = (16 * (nc + 32) + 31 <= tq) ? p1[r] : -INFINITY;
;                         }
.LBB0_780:
	global_load_dwordx4 v[0:3], v[88:89], off offset:-64
	global_load_dwordx4 v[94:97], v[88:89], off offset:-32
	global_load_dwordx4 v[172:175], v[88:89], off
	global_load_dwordx4 v[176:179], v[88:89], off offset:32
	v_add_u32_e32 v90, s74, v92
	v_add_u32_e32 v90, 0x21400, v90
	ds_read_b64 v[90:91], v90
	s_andn2_b64 vcc, exec, s[84:85]
	s_waitcnt vmcnt(3) lgkmcnt(8)
	v_mfma_f32_32x32x16_bf16 v[16:31], v[32:35], v[0:3], 0
	s_waitcnt lgkmcnt(6)
	v_mfma_f32_32x32x16_bf16 v[0:15], v[40:43], v[0:3], 0
	s_waitcnt vmcnt(2)
	v_mfma_f32_32x32x16_bf16 v[16:31], v[36:39], v[94:97], v[16:31]
	s_waitcnt lgkmcnt(5)
	v_mfma_f32_32x32x16_bf16 v[0:15], v[44:47], v[94:97], v[0:15]
	s_waitcnt vmcnt(1) lgkmcnt(4)
	v_mfma_f32_32x32x16_bf16 v[16:31], v[48:51], v[172:175], v[16:31]
	s_waitcnt lgkmcnt(2)
	v_mfma_f32_32x32x16_bf16 v[0:15], v[56:59], v[172:175], v[0:15]
	s_waitcnt vmcnt(0)
	v_mfma_f32_32x32x16_bf16 v[16:31], v[52:55], v[176:179], v[16:31]
	s_waitcnt lgkmcnt(1)
	v_mfma_f32_32x32x16_bf16 v[0:15], v[60:63], v[176:179], v[0:15]
	s_cbranch_vccnz .LBB0_779
	s_nop 8
	v_cndmask_b32_e64 v16, v16, v249, s[4:5]
	s_nop 0
	v_cndmask_b32_e64 v0, v0, v249, s[6:7]
	v_cndmask_b32_e64 v17, v17, v249, s[8:9]
	v_cndmask_b32_e64 v1, v1, v249, s[10:11]
	v_cndmask_b32_e64 v18, v18, v249, s[12:13]
	v_cndmask_b32_e64 v2, v2, v249, s[14:15]
	v_cndmask_b32_e64 v19, v19, v249, s[16:17]
	v_cndmask_b32_e64 v3, v3, v249, s[18:19]
	v_cndmask_b32_e64 v20, v20, v249, s[20:21]
	v_cndmask_b32_e64 v4, v4, v249, s[22:23]
	v_cndmask_b32_e64 v21, v21, v249, s[24:25]
	v_cndmask_b32_e64 v5, v5, v249, s[26:27]
	v_cndmask_b32_e64 v22, v22, v249, s[28:29]
	v_cndmask_b32_e64 v6, v6, v249, s[30:31]
	v_cndmask_b32_e64 v23, v23, v249, s[34:35]
	v_cndmask_b32_e64 v7, v7, v249, s[36:37]
	v_cndmask_b32_e64 v24, v24, v249, s[38:39]
	v_cndmask_b32_e64 v8, v8, v249, s[40:41]
	v_cndmask_b32_e64 v25, v25, v249, s[42:43]
	v_cndmask_b32_e64 v9, v9, v249, s[44:45]
	v_cndmask_b32_e64 v26, v26, v249, s[46:47]
	v_cndmask_b32_e64 v10, v10, v249, s[48:49]
	v_cndmask_b32_e64 v27, v27, v249, s[50:51]
	v_cndmask_b32_e64 v11, v11, v249, s[52:53]
	v_cndmask_b32_e64 v28, v28, v249, s[54:55]
	v_cndmask_b32_e64 v12, v12, v249, s[56:57]
	v_cndmask_b32_e64 v29, v29, v249, s[58:59]
	v_cndmask_b32_e64 v13, v13, v249, s[60:61]
	v_cndmask_b32_e64 v30, v30, v249, s[62:63]
	v_cndmask_b32_e64 v14, v14, v249, s[64:65]
	v_cndmask_b32_e64 v31, v31, v249, s[66:67]
	v_cndmask_b32_e64 v15, v15, v249, s[68:69]
	s_branch .LBB0_779
